# S item: 96 ds_bpermute butterfly steps of the 16 partial sums replaced by a DPP wave reduction, lane 63 writes the totals with 4 ds_write_b128
# speedup vs baseline: 1.0045x; 1.0045x over previous
.Ls_hoist_skip_c1:
	s_mov_b64 exec, s[100:101]
	s_nop 1
	v_add_f32_dpp v10, v174, v174 quad_perm:[1,0,3,2] row_mask:0xf bank_mask:0xf
	v_add_f32_dpp v11, v175, v175 quad_perm:[1,0,3,2] row_mask:0xf bank_mask:0xf
	v_add_f32_dpp v12, v170, v170 quad_perm:[1,0,3,2] row_mask:0xf bank_mask:0xf
	v_add_f32_dpp v13, v171, v171 quad_perm:[1,0,3,2] row_mask:0xf bank_mask:0xf
	v_add_f32_dpp v14, v8, v8 quad_perm:[1,0,3,2] row_mask:0xf bank_mask:0xf
	v_add_f32_dpp v15, v9, v9 quad_perm:[1,0,3,2] row_mask:0xf bank_mask:0xf
	v_add_f32_dpp v16, v6, v6 quad_perm:[1,0,3,2] row_mask:0xf bank_mask:0xf
	v_add_f32_dpp v17, v7, v7 quad_perm:[1,0,3,2] row_mask:0xf bank_mask:0xf
	v_add_f32_dpp v18, v166, v166 quad_perm:[1,0,3,2] row_mask:0xf bank_mask:0xf
	v_add_f32_dpp v19, v167, v167 quad_perm:[1,0,3,2] row_mask:0xf bank_mask:0xf
	v_add_f32_dpp v20, v168, v168 quad_perm:[1,0,3,2] row_mask:0xf bank_mask:0xf
	v_add_f32_dpp v21, v169, v169 quad_perm:[1,0,3,2] row_mask:0xf bank_mask:0xf
	v_add_f32_dpp v22, v2, v2 quad_perm:[1,0,3,2] row_mask:0xf bank_mask:0xf
	v_add_f32_dpp v23, v3, v3 quad_perm:[1,0,3,2] row_mask:0xf bank_mask:0xf
	v_add_f32_dpp v24, v4, v4 quad_perm:[1,0,3,2] row_mask:0xf bank_mask:0xf
	v_add_f32_dpp v25, v5, v5 quad_perm:[1,0,3,2] row_mask:0xf bank_mask:0xf
	v_add_f32_dpp v10, v10, v10 quad_perm:[2,3,0,1] row_mask:0xf bank_mask:0xf
	v_add_f32_dpp v11, v11, v11 quad_perm:[2,3,0,1] row_mask:0xf bank_mask:0xf
	v_add_f32_dpp v12, v12, v12 quad_perm:[2,3,0,1] row_mask:0xf bank_mask:0xf
	v_add_f32_dpp v13, v13, v13 quad_perm:[2,3,0,1] row_mask:0xf bank_mask:0xf
	v_add_f32_dpp v14, v14, v14 quad_perm:[2,3,0,1] row_mask:0xf bank_mask:0xf
	v_add_f32_dpp v15, v15, v15 quad_perm:[2,3,0,1] row_mask:0xf bank_mask:0xf
	v_add_f32_dpp v16, v16, v16 quad_perm:[2,3,0,1] row_mask:0xf bank_mask:0xf
	v_add_f32_dpp v17, v17, v17 quad_perm:[2,3,0,1] row_mask:0xf bank_mask:0xf
	v_add_f32_dpp v18, v18, v18 quad_perm:[2,3,0,1] row_mask:0xf bank_mask:0xf
	v_add_f32_dpp v19, v19, v19 quad_perm:[2,3,0,1] row_mask:0xf bank_mask:0xf
	v_add_f32_dpp v20, v20, v20 quad_perm:[2,3,0,1] row_mask:0xf bank_mask:0xf
	v_add_f32_dpp v21, v21, v21 quad_perm:[2,3,0,1] row_mask:0xf bank_mask:0xf
	v_add_f32_dpp v22, v22, v22 quad_perm:[2,3,0,1] row_mask:0xf bank_mask:0xf
	v_add_f32_dpp v23, v23, v23 quad_perm:[2,3,0,1] row_mask:0xf bank_mask:0xf
	v_add_f32_dpp v24, v24, v24 quad_perm:[2,3,0,1] row_mask:0xf bank_mask:0xf
	v_add_f32_dpp v25, v25, v25 quad_perm:[2,3,0,1] row_mask:0xf bank_mask:0xf
	v_add_f32_dpp v10, v10, v10 row_half_mirror row_mask:0xf bank_mask:0xf
	v_add_f32_dpp v11, v11, v11 row_half_mirror row_mask:0xf bank_mask:0xf
	v_add_f32_dpp v12, v12, v12 row_half_mirror row_mask:0xf bank_mask:0xf
	v_add_f32_dpp v13, v13, v13 row_half_mirror row_mask:0xf bank_mask:0xf
	v_add_f32_dpp v14, v14, v14 row_half_mirror row_mask:0xf bank_mask:0xf
	v_add_f32_dpp v15, v15, v15 row_half_mirror row_mask:0xf bank_mask:0xf
	v_add_f32_dpp v16, v16, v16 row_half_mirror row_mask:0xf bank_mask:0xf
	v_add_f32_dpp v17, v17, v17 row_half_mirror row_mask:0xf bank_mask:0xf
	v_add_f32_dpp v18, v18, v18 row_half_mirror row_mask:0xf bank_mask:0xf
	v_add_f32_dpp v19, v19, v19 row_half_mirror row_mask:0xf bank_mask:0xf
	v_add_f32_dpp v20, v20, v20 row_half_mirror row_mask:0xf bank_mask:0xf
	v_add_f32_dpp v21, v21, v21 row_half_mirror row_mask:0xf bank_mask:0xf
	v_add_f32_dpp v22, v22, v22 row_half_mirror row_mask:0xf bank_mask:0xf
	v_add_f32_dpp v23, v23, v23 row_half_mirror row_mask:0xf bank_mask:0xf
	v_add_f32_dpp v24, v24, v24 row_half_mirror row_mask:0xf bank_mask:0xf
	v_add_f32_dpp v25, v25, v25 row_half_mirror row_mask:0xf bank_mask:0xf
	v_add_f32_dpp v10, v10, v10 row_mirror row_mask:0xf bank_mask:0xf
	v_add_f32_dpp v11, v11, v11 row_mirror row_mask:0xf bank_mask:0xf
	v_add_f32_dpp v12, v12, v12 row_mirror row_mask:0xf bank_mask:0xf
	v_add_f32_dpp v13, v13, v13 row_mirror row_mask:0xf bank_mask:0xf
	v_add_f32_dpp v14, v14, v14 row_mirror row_mask:0xf bank_mask:0xf
	v_add_f32_dpp v15, v15, v15 row_mirror row_mask:0xf bank_mask:0xf
	v_add_f32_dpp v16, v16, v16 row_mirror row_mask:0xf bank_mask:0xf
	v_add_f32_dpp v17, v17, v17 row_mirror row_mask:0xf bank_mask:0xf
	v_add_f32_dpp v18, v18, v18 row_mirror row_mask:0xf bank_mask:0xf
	v_add_f32_dpp v19, v19, v19 row_mirror row_mask:0xf bank_mask:0xf
	v_add_f32_dpp v20, v20, v20 row_mirror row_mask:0xf bank_mask:0xf
	v_add_f32_dpp v21, v21, v21 row_mirror row_mask:0xf bank_mask:0xf
	v_add_f32_dpp v22, v22, v22 row_mirror row_mask:0xf bank_mask:0xf
	v_add_f32_dpp v23, v23, v23 row_mirror row_mask:0xf bank_mask:0xf
	v_add_f32_dpp v24, v24, v24 row_mirror row_mask:0xf bank_mask:0xf
	v_add_f32_dpp v25, v25, v25 row_mirror row_mask:0xf bank_mask:0xf
	v_add_f32_dpp v10, v10, v10 row_bcast:15 row_mask:0xa bank_mask:0xf
	v_add_f32_dpp v11, v11, v11 row_bcast:15 row_mask:0xa bank_mask:0xf
	v_add_f32_dpp v12, v12, v12 row_bcast:15 row_mask:0xa bank_mask:0xf
	v_add_f32_dpp v13, v13, v13 row_bcast:15 row_mask:0xa bank_mask:0xf
	v_add_f32_dpp v14, v14, v14 row_bcast:15 row_mask:0xa bank_mask:0xf
	v_add_f32_dpp v15, v15, v15 row_bcast:15 row_mask:0xa bank_mask:0xf
	v_add_f32_dpp v16, v16, v16 row_bcast:15 row_mask:0xa bank_mask:0xf
	v_add_f32_dpp v17, v17, v17 row_bcast:15 row_mask:0xa bank_mask:0xf
	v_add_f32_dpp v18, v18, v18 row_bcast:15 row_mask:0xa bank_mask:0xf
	v_add_f32_dpp v19, v19, v19 row_bcast:15 row_mask:0xa bank_mask:0xf
	v_add_f32_dpp v20, v20, v20 row_bcast:15 row_mask:0xa bank_mask:0xf
	v_add_f32_dpp v21, v21, v21 row_bcast:15 row_mask:0xa bank_mask:0xf
	v_add_f32_dpp v22, v22, v22 row_bcast:15 row_mask:0xa bank_mask:0xf
	v_add_f32_dpp v23, v23, v23 row_bcast:15 row_mask:0xa bank_mask:0xf
	v_add_f32_dpp v24, v24, v24 row_bcast:15 row_mask:0xa bank_mask:0xf
	v_add_f32_dpp v25, v25, v25 row_bcast:15 row_mask:0xa bank_mask:0xf
	v_add_f32_dpp v10, v10, v10 row_bcast:31 row_mask:0xc bank_mask:0xf
	v_add_f32_dpp v11, v11, v11 row_bcast:31 row_mask:0xc bank_mask:0xf
	v_add_f32_dpp v12, v12, v12 row_bcast:31 row_mask:0xc bank_mask:0xf
	v_add_f32_dpp v13, v13, v13 row_bcast:31 row_mask:0xc bank_mask:0xf
	v_add_f32_dpp v14, v14, v14 row_bcast:31 row_mask:0xc bank_mask:0xf
	v_add_f32_dpp v15, v15, v15 row_bcast:31 row_mask:0xc bank_mask:0xf
	v_add_f32_dpp v16, v16, v16 row_bcast:31 row_mask:0xc bank_mask:0xf
	v_add_f32_dpp v17, v17, v17 row_bcast:31 row_mask:0xc bank_mask:0xf
	v_add_f32_dpp v18, v18, v18 row_bcast:31 row_mask:0xc bank_mask:0xf
	v_add_f32_dpp v19, v19, v19 row_bcast:31 row_mask:0xc bank_mask:0xf
	v_add_f32_dpp v20, v20, v20 row_bcast:31 row_mask:0xc bank_mask:0xf
	v_add_f32_dpp v21, v21, v21 row_bcast:31 row_mask:0xc bank_mask:0xf
	v_add_f32_dpp v22, v22, v22 row_bcast:31 row_mask:0xc bank_mask:0xf
	v_add_f32_dpp v23, v23, v23 row_bcast:31 row_mask:0xc bank_mask:0xf
	v_add_f32_dpp v24, v24, v24 row_bcast:31 row_mask:0xc bank_mask:0xf
	v_add_f32_dpp v25, v25, v25 row_bcast:31 row_mask:0xc bank_mask:0xf
	v_and_b32_e32 v34, 63, v164
	v_cmp_eq_u32_e32 vcc, 63, v34
	s_and_saveexec_b64 s[2:3], vcc
	s_cbranch_execz .LBB0_789
	v_add_u32_e32 v34, -31, v164
	v_add_u32_e32 v34, 0x16000, v34
	ds_write_b128 v34, v[10:13]
	ds_write_b128 v34, v[14:17] offset:16
	ds_write_b128 v34, v[18:21] offset:32
	ds_write_b128 v34, v[22:25] offset:48

.Ls_hoist_skip_c2:
	s_mov_b64 exec, s[100:101]
	s_nop 1
	v_add_f32_dpp v10, v140, v140 quad_perm:[1,0,3,2] row_mask:0xf bank_mask:0xf
	v_add_f32_dpp v11, v141, v141 quad_perm:[1,0,3,2] row_mask:0xf bank_mask:0xf
	v_add_f32_dpp v12, v136, v136 quad_perm:[1,0,3,2] row_mask:0xf bank_mask:0xf
	v_add_f32_dpp v13, v137, v137 quad_perm:[1,0,3,2] row_mask:0xf bank_mask:0xf
	v_add_f32_dpp v14, v8, v8 quad_perm:[1,0,3,2] row_mask:0xf bank_mask:0xf
	v_add_f32_dpp v15, v9, v9 quad_perm:[1,0,3,2] row_mask:0xf bank_mask:0xf
	v_add_f32_dpp v16, v6, v6 quad_perm:[1,0,3,2] row_mask:0xf bank_mask:0xf
	v_add_f32_dpp v17, v7, v7 quad_perm:[1,0,3,2] row_mask:0xf bank_mask:0xf
	v_add_f32_dpp v18, v132, v132 quad_perm:[1,0,3,2] row_mask:0xf bank_mask:0xf
	v_add_f32_dpp v19, v133, v133 quad_perm:[1,0,3,2] row_mask:0xf bank_mask:0xf
	v_add_f32_dpp v20, v134, v134 quad_perm:[1,0,3,2] row_mask:0xf bank_mask:0xf
	v_add_f32_dpp v21, v135, v135 quad_perm:[1,0,3,2] row_mask:0xf bank_mask:0xf
	v_add_f32_dpp v22, v2, v2 quad_perm:[1,0,3,2] row_mask:0xf bank_mask:0xf
	v_add_f32_dpp v23, v3, v3 quad_perm:[1,0,3,2] row_mask:0xf bank_mask:0xf
	v_add_f32_dpp v24, v4, v4 quad_perm:[1,0,3,2] row_mask:0xf bank_mask:0xf
	v_add_f32_dpp v25, v5, v5 quad_perm:[1,0,3,2] row_mask:0xf bank_mask:0xf
	v_add_f32_dpp v10, v10, v10 quad_perm:[2,3,0,1] row_mask:0xf bank_mask:0xf
	v_add_f32_dpp v11, v11, v11 quad_perm:[2,3,0,1] row_mask:0xf bank_mask:0xf
	v_add_f32_dpp v12, v12, v12 quad_perm:[2,3,0,1] row_mask:0xf bank_mask:0xf
	v_add_f32_dpp v13, v13, v13 quad_perm:[2,3,0,1] row_mask:0xf bank_mask:0xf
	v_add_f32_dpp v14, v14, v14 quad_perm:[2,3,0,1] row_mask:0xf bank_mask:0xf
	v_add_f32_dpp v15, v15, v15 quad_perm:[2,3,0,1] row_mask:0xf bank_mask:0xf
	v_add_f32_dpp v16, v16, v16 quad_perm:[2,3,0,1] row_mask:0xf bank_mask:0xf
	v_add_f32_dpp v17, v17, v17 quad_perm:[2,3,0,1] row_mask:0xf bank_mask:0xf
	v_add_f32_dpp v18, v18, v18 quad_perm:[2,3,0,1] row_mask:0xf bank_mask:0xf
	v_add_f32_dpp v19, v19, v19 quad_perm:[2,3,0,1] row_mask:0xf bank_mask:0xf
	v_add_f32_dpp v20, v20, v20 quad_perm:[2,3,0,1] row_mask:0xf bank_mask:0xf
	v_add_f32_dpp v21, v21, v21 quad_perm:[2,3,0,1] row_mask:0xf bank_mask:0xf
	v_add_f32_dpp v22, v22, v22 quad_perm:[2,3,0,1] row_mask:0xf bank_mask:0xf
	v_add_f32_dpp v23, v23, v23 quad_perm:[2,3,0,1] row_mask:0xf bank_mask:0xf
	v_add_f32_dpp v24, v24, v24 quad_perm:[2,3,0,1] row_mask:0xf bank_mask:0xf
	v_add_f32_dpp v25, v25, v25 quad_perm:[2,3,0,1] row_mask:0xf bank_mask:0xf
	v_add_f32_dpp v10, v10, v10 row_half_mirror row_mask:0xf bank_mask:0xf
	v_add_f32_dpp v11, v11, v11 row_half_mirror row_mask:0xf bank_mask:0xf
	v_add_f32_dpp v12, v12, v12 row_half_mirror row_mask:0xf bank_mask:0xf
	v_add_f32_dpp v13, v13, v13 row_half_mirror row_mask:0xf bank_mask:0xf
	v_add_f32_dpp v14, v14, v14 row_half_mirror row_mask:0xf bank_mask:0xf
	v_add_f32_dpp v15, v15, v15 row_half_mirror row_mask:0xf bank_mask:0xf
	v_add_f32_dpp v16, v16, v16 row_half_mirror row_mask:0xf bank_mask:0xf
	v_add_f32_dpp v17, v17, v17 row_half_mirror row_mask:0xf bank_mask:0xf
	v_add_f32_dpp v18, v18, v18 row_half_mirror row_mask:0xf bank_mask:0xf
	v_add_f32_dpp v19, v19, v19 row_half_mirror row_mask:0xf bank_mask:0xf
	v_add_f32_dpp v20, v20, v20 row_half_mirror row_mask:0xf bank_mask:0xf
	v_add_f32_dpp v21, v21, v21 row_half_mirror row_mask:0xf bank_mask:0xf
	v_add_f32_dpp v22, v22, v22 row_half_mirror row_mask:0xf bank_mask:0xf
	v_add_f32_dpp v23, v23, v23 row_half_mirror row_mask:0xf bank_mask:0xf
	v_add_f32_dpp v24, v24, v24 row_half_mirror row_mask:0xf bank_mask:0xf
	v_add_f32_dpp v25, v25, v25 row_half_mirror row_mask:0xf bank_mask:0xf
	v_add_f32_dpp v10, v10, v10 row_mirror row_mask:0xf bank_mask:0xf
	v_add_f32_dpp v11, v11, v11 row_mirror row_mask:0xf bank_mask:0xf
	v_add_f32_dpp v12, v12, v12 row_mirror row_mask:0xf bank_mask:0xf
	v_add_f32_dpp v13, v13, v13 row_mirror row_mask:0xf bank_mask:0xf
	v_add_f32_dpp v14, v14, v14 row_mirror row_mask:0xf bank_mask:0xf
	v_add_f32_dpp v15, v15, v15 row_mirror row_mask:0xf bank_mask:0xf
	v_add_f32_dpp v16, v16, v16 row_mirror row_mask:0xf bank_mask:0xf
	v_add_f32_dpp v17, v17, v17 row_mirror row_mask:0xf bank_mask:0xf
	v_add_f32_dpp v18, v18, v18 row_mirror row_mask:0xf bank_mask:0xf
	v_add_f32_dpp v19, v19, v19 row_mirror row_mask:0xf bank_mask:0xf
	v_add_f32_dpp v20, v20, v20 row_mirror row_mask:0xf bank_mask:0xf
	v_add_f32_dpp v21, v21, v21 row_mirror row_mask:0xf bank_mask:0xf
	v_add_f32_dpp v22, v22, v22 row_mirror row_mask:0xf bank_mask:0xf
	v_add_f32_dpp v23, v23, v23 row_mirror row_mask:0xf bank_mask:0xf
	v_add_f32_dpp v24, v24, v24 row_mirror row_mask:0xf bank_mask:0xf
	v_add_f32_dpp v25, v25, v25 row_mirror row_mask:0xf bank_mask:0xf
	v_add_f32_dpp v10, v10, v10 row_bcast:15 row_mask:0xa bank_mask:0xf
	v_add_f32_dpp v11, v11, v11 row_bcast:15 row_mask:0xa bank_mask:0xf
	v_add_f32_dpp v12, v12, v12 row_bcast:15 row_mask:0xa bank_mask:0xf
	v_add_f32_dpp v13, v13, v13 row_bcast:15 row_mask:0xa bank_mask:0xf
	v_add_f32_dpp v14, v14, v14 row_bcast:15 row_mask:0xa bank_mask:0xf
	v_add_f32_dpp v15, v15, v15 row_bcast:15 row_mask:0xa bank_mask:0xf
	v_add_f32_dpp v16, v16, v16 row_bcast:15 row_mask:0xa bank_mask:0xf
	v_add_f32_dpp v17, v17, v17 row_bcast:15 row_mask:0xa bank_mask:0xf
	v_add_f32_dpp v18, v18, v18 row_bcast:15 row_mask:0xa bank_mask:0xf
	v_add_f32_dpp v19, v19, v19 row_bcast:15 row_mask:0xa bank_mask:0xf
	v_add_f32_dpp v20, v20, v20 row_bcast:15 row_mask:0xa bank_mask:0xf
	v_add_f32_dpp v21, v21, v21 row_bcast:15 row_mask:0xa bank_mask:0xf
	v_add_f32_dpp v22, v22, v22 row_bcast:15 row_mask:0xa bank_mask:0xf
	v_add_f32_dpp v23, v23, v23 row_bcast:15 row_mask:0xa bank_mask:0xf
	v_add_f32_dpp v24, v24, v24 row_bcast:15 row_mask:0xa bank_mask:0xf
	v_add_f32_dpp v25, v25, v25 row_bcast:15 row_mask:0xa bank_mask:0xf
	v_add_f32_dpp v10, v10, v10 row_bcast:31 row_mask:0xc bank_mask:0xf
	v_add_f32_dpp v11, v11, v11 row_bcast:31 row_mask:0xc bank_mask:0xf
	v_add_f32_dpp v12, v12, v12 row_bcast:31 row_mask:0xc bank_mask:0xf
	v_add_f32_dpp v13, v13, v13 row_bcast:31 row_mask:0xc bank_mask:0xf
	v_add_f32_dpp v14, v14, v14 row_bcast:31 row_mask:0xc bank_mask:0xf
	v_add_f32_dpp v15, v15, v15 row_bcast:31 row_mask:0xc bank_mask:0xf
	v_add_f32_dpp v16, v16, v16 row_bcast:31 row_mask:0xc bank_mask:0xf
	v_add_f32_dpp v17, v17, v17 row_bcast:31 row_mask:0xc bank_mask:0xf
	v_add_f32_dpp v18, v18, v18 row_bcast:31 row_mask:0xc bank_mask:0xf
	v_add_f32_dpp v19, v19, v19 row_bcast:31 row_mask:0xc bank_mask:0xf
	v_add_f32_dpp v20, v20, v20 row_bcast:31 row_mask:0xc bank_mask:0xf
	v_add_f32_dpp v21, v21, v21 row_bcast:31 row_mask:0xc bank_mask:0xf
	v_add_f32_dpp v22, v22, v22 row_bcast:31 row_mask:0xc bank_mask:0xf
	v_add_f32_dpp v23, v23, v23 row_bcast:31 row_mask:0xc bank_mask:0xf
	v_add_f32_dpp v24, v24, v24 row_bcast:31 row_mask:0xc bank_mask:0xf
	v_add_f32_dpp v25, v25, v25 row_bcast:31 row_mask:0xc bank_mask:0xf
	v_and_b32_e32 v34, 63, v130
	v_cmp_eq_u32_e32 vcc, 63, v34
	s_and_saveexec_b64 s[2:3], vcc
	s_cbranch_execz .LBB0_859
	v_add_u32_e32 v34, -31, v130
	v_add_u32_e32 v34, 0x16000, v34
	ds_write_b128 v34, v[10:13]
	ds_write_b128 v34, v[14:17] offset:16
	ds_write_b128 v34, v[18:21] offset:32
	ds_write_b128 v34, v[22:25] offset:48
